# EpiStNorm row-stat readback: 16 serialized LDS reads+branches replaced by two batched groups with cndmask select
# baseline (speedup 1.0000x reference)
.LBB0_456:
	s_waitcnt lgkmcnt(0)
	s_barrier
	v_add_u32_e32 v251, 0x20000, v163
	ds_read_b128 v[208:211], v251
	ds_read_b128 v[212:215], v251 offset:256
	ds_read_b128 v[216:219], v251 offset:512
	ds_read_b128 v[220:223], v251 offset:768
	ds_read_b128 v[224:227], v251 offset:2048
	ds_read_b128 v[228:231], v251 offset:2304
	ds_read_b128 v[232:235], v251 offset:2560
	ds_read_b128 v[236:239], v251 offset:2816
	s_waitcnt lgkmcnt(0)
	v_add_f32_e32 v240, v209, v208
	v_add_f32_e32 v241, v210, v211
	v_add_f32_e32 v242, v213, v212
	v_add_f32_e32 v243, v214, v215
	v_add_f32_e32 v244, v217, v216
	v_add_f32_e32 v245, v218, v219
	v_add_f32_e32 v246, v221, v220
	v_add_f32_e32 v247, v222, v223
	v_add_f32_e32 v248, v225, v224
	v_add_f32_e32 v249, v226, v227
	v_add_f32_e32 v250, v229, v228
	v_add_f32_e32 v204, v230, v231
	v_add_f32_e32 v205, v233, v232
	v_add_f32_e32 v206, v234, v235
	v_add_f32_e32 v207, v237, v236
	v_add_f32_e32 v201, v238, v239
	ds_read_b128 v[208:211], v251 offset:4096
	ds_read_b128 v[212:215], v251 offset:4352
	ds_read_b128 v[216:219], v251 offset:4608
	ds_read_b128 v[220:223], v251 offset:4864
	ds_read_b128 v[224:227], v251 offset:6144
	ds_read_b128 v[228:231], v251 offset:6400
	ds_read_b128 v[232:235], v251 offset:6656
	ds_read_b128 v[236:239], v251 offset:6912
	v_add_f32_e32 v240, v240, v241
	v_add_f32_e32 v242, v242, v243
	v_add_f32_e32 v244, v244, v245
	v_add_f32_e32 v246, v246, v247
	v_add_f32_e32 v248, v248, v249
	v_add_f32_e32 v250, v250, v204
	v_add_f32_e32 v205, v205, v206
	v_add_f32_e32 v207, v207, v201
	v_fmamk_f32 v240, v240, 0x3c000000, v196
	v_fmamk_f32 v242, v242, 0x3c000000, v196
	v_fmamk_f32 v244, v244, 0x3c000000, v196
	v_fmamk_f32 v246, v246, 0x3c000000, v196
	v_fmamk_f32 v248, v248, 0x3c000000, v196
	v_fmamk_f32 v250, v250, 0x3c000000, v196
	v_fmamk_f32 v205, v205, 0x3c000000, v196
	v_fmamk_f32 v207, v207, 0x3c000000, v196
	v_rsq_f32_e32 v240, v240
	v_rsq_f32_e32 v242, v242
	v_rsq_f32_e32 v244, v244
	v_rsq_f32_e32 v246, v246
	v_rsq_f32_e32 v248, v248
	v_rsq_f32_e32 v250, v250
	v_rsq_f32_e32 v205, v205
	v_rsq_f32_e32 v207, v207
	v_cndmask_b32_e64 v188, v240, 1.0, s[6:7]
	v_cndmask_b32_e64 v176, v242, 1.0, s[6:7]
	v_cndmask_b32_e64 v174, v244, 1.0, s[6:7]
	v_cndmask_b32_e64 v164, v246, 1.0, s[6:7]
	v_cndmask_b32_e64 v172, v248, 1.0, s[6:7]
	v_cndmask_b32_e64 v162, v250, 1.0, s[6:7]
	v_cndmask_b32_e64 v160, v205, 1.0, s[6:7]
	v_cndmask_b32_e64 v156, v207, 1.0, s[6:7]
	s_waitcnt lgkmcnt(0)
	v_add_f32_e32 v240, v209, v208
	v_add_f32_e32 v241, v210, v211
	v_add_f32_e32 v242, v213, v212
	v_add_f32_e32 v243, v214, v215
	v_add_f32_e32 v244, v217, v216
	v_add_f32_e32 v245, v218, v219
	v_add_f32_e32 v246, v221, v220
	v_add_f32_e32 v247, v222, v223
	v_add_f32_e32 v248, v225, v224
	v_add_f32_e32 v249, v226, v227
	v_add_f32_e32 v250, v229, v228
	v_add_f32_e32 v204, v230, v231
	v_add_f32_e32 v205, v233, v232
	v_add_f32_e32 v206, v234, v235
	v_add_f32_e32 v207, v237, v236
	v_add_f32_e32 v201, v238, v239
	v_add_f32_e32 v240, v240, v241
	v_add_f32_e32 v242, v242, v243
	v_add_f32_e32 v244, v244, v245
	v_add_f32_e32 v246, v246, v247
	v_add_f32_e32 v248, v248, v249
	v_add_f32_e32 v250, v250, v204
	v_add_f32_e32 v205, v205, v206
	v_add_f32_e32 v207, v207, v201
	v_fmamk_f32 v240, v240, 0x3c000000, v196
	v_fmamk_f32 v242, v242, 0x3c000000, v196
	v_fmamk_f32 v244, v244, 0x3c000000, v196
	v_fmamk_f32 v246, v246, 0x3c000000, v196
	v_fmamk_f32 v248, v248, 0x3c000000, v196
	v_fmamk_f32 v250, v250, 0x3c000000, v196
	v_fmamk_f32 v205, v205, 0x3c000000, v196
	v_fmamk_f32 v207, v207, 0x3c000000, v196
	v_rsq_f32_e32 v240, v240
	v_rsq_f32_e32 v242, v242
	v_rsq_f32_e32 v244, v244
	v_rsq_f32_e32 v246, v246
	v_rsq_f32_e32 v248, v248
	v_rsq_f32_e32 v250, v250
	v_rsq_f32_e32 v205, v205
	v_rsq_f32_e32 v207, v207
	v_cndmask_b32_e64 v190, v240, 1.0, s[8:9]
	v_cndmask_b32_e64 v186, v242, 1.0, s[8:9]
	v_cndmask_b32_e64 v184, v244, 1.0, s[8:9]
	v_cndmask_b32_e64 v170, v246, 1.0, s[8:9]
	v_cndmask_b32_e64 v182, v248, 1.0, s[8:9]
	v_cndmask_b32_e64 v168, v250, 1.0, s[8:9]
	v_cndmask_b32_e64 v166, v205, 1.0, s[8:9]
	v_cndmask_b32_e64 v158, v207, 1.0, s[8:9]
.LBB0_473:
	s_and_b64 s[6:7], s[62:63], exec
	s_mov_b32 s6, 0x11000000
	s_cselect_b32 s6, s6, 0x23000000
	s_add_u32 s8, s96, s6
	s_addc_u32 s9, s97, 0
	s_and_b64 s[6:7], s[62:63], exec
	s_movk_i32 s6, 0x1200
	s_cselect_b32 s6, s6, 0x800
	s_lshl_b32 s7, s93, 8
	s_and_b64 s[16:17], s[62:63], exec
	s_cselect_b32 s16, 0, s90
	s_add_i32 s7, s7, s16
	v_add_u32_e32 v180, s7, v161
	v_lshl_add_u32 v167, s92, 8, v157
	v_ashrrev_i32_e32 v181, 31, v180
	v_lshl_add_u64 v[180:181], v[180:181], 1, s[8:9]
	v_mad_i64_i32 v[192:193], s[8:9], s6, v167, 0
	v_pk_mul_f32 v[128:129], v[128:129], v[146:147]
	v_pk_mul_f32 v[126:127], v[126:127], v[140:141]
	v_pk_mul_f32 v[124:125], v[124:125], v[144:145]
	v_pk_mul_f32 v[122:123], v[122:123], v[142:143]
	v_lshl_add_u64 v[192:193], v[192:193], 1, v[180:181]
	v_pk_mul_f32 v[128:129], v[128:129], v[188:189] op_sel_hi:[1,0]
	v_pk_mul_f32 v[126:127], v[126:127], v[188:189] op_sel_hi:[1,0]
	v_pk_mul_f32 v[194:195], v[124:125], v[188:189] op_sel_hi:[1,0]
	v_pk_mul_f32 v[124:125], v[122:123], v[188:189] op_sel_hi:[1,0]
	v_cvt_pk_bf16_f32 v122, v126, v127
	v_cvt_pk_bf16_f32 v123, v128, v129
	v_pk_mul_f32 v[118:119], v[118:119], v[148:149]
	v_pk_mul_f32 v[112:113], v[112:113], v[154:155]
	v_pk_mul_f32 v[110:111], v[110:111], v[150:151]
	v_cvt_pk_bf16_f32 v124, v124, v125
	v_cvt_pk_bf16_f32 v125, v194, v195
	global_store_dwordx4 v[192:193], v[122:125], off
	v_pk_mul_f32 v[120:121], v[120:121], v[152:153]
	v_pk_mul_f32 v[118:119], v[118:119], v[190:191] op_sel_hi:[1,0]
	v_pk_mul_f32 v[122:123], v[112:113], v[190:191] op_sel_hi:[1,0]
	v_pk_mul_f32 v[112:113], v[110:111], v[190:191] op_sel_hi:[1,0]
	v_cvt_pk_bf16_f32 v110, v118, v119
	v_pk_mul_f32 v[120:121], v[120:121], v[190:191] op_sel_hi:[1,0]
	v_pk_mul_f32 v[114:115], v[114:115], v[140:141]
	v_cvt_pk_bf16_f32 v111, v120, v121
	v_cvt_pk_bf16_f32 v112, v112, v113
	v_cvt_pk_bf16_f32 v113, v122, v123
	global_store_dwordx4 v[192:193], v[110:113], off offset:256
	v_pk_mul_f32 v[108:109], v[108:109], v[144:145]
	v_pk_mul_f32 v[106:107], v[106:107], v[142:143]
	v_or_b32_e32 v110, 16, v167
	v_mad_i64_i32 v[110:111], s[8:9], s6, v110, 0
	v_pk_mul_f32 v[112:113], v[116:117], v[146:147]
	v_lshl_add_u64 v[110:111], v[110:111], 1, v[180:181]
	v_pk_mul_f32 v[112:113], v[112:113], v[176:177] op_sel_hi:[1,0]
	v_pk_mul_f32 v[114:115], v[114:115], v[176:177] op_sel_hi:[1,0]
	v_pk_mul_f32 v[116:117], v[108:109], v[176:177] op_sel_hi:[1,0]
	v_pk_mul_f32 v[108:109], v[106:107], v[176:177] op_sel_hi:[1,0]
	v_cvt_pk_bf16_f32 v106, v114, v115
	v_cvt_pk_bf16_f32 v107, v112, v113
	v_pk_mul_f32 v[102:103], v[102:103], v[148:149]
	v_pk_mul_f32 v[96:97], v[96:97], v[154:155]
	v_pk_mul_f32 v[94:95], v[94:95], v[150:151]
	v_cvt_pk_bf16_f32 v108, v108, v109
	v_cvt_pk_bf16_f32 v109, v116, v117
	global_store_dwordx4 v[110:111], v[106:109], off
	v_pk_mul_f32 v[104:105], v[104:105], v[152:153]
	v_pk_mul_f32 v[102:103], v[102:103], v[186:187] op_sel_hi:[1,0]
	v_pk_mul_f32 v[106:107], v[96:97], v[186:187] op_sel_hi:[1,0]
	v_pk_mul_f32 v[96:97], v[94:95], v[186:187] op_sel_hi:[1,0]
	v_cvt_pk_bf16_f32 v94, v102, v103
	v_pk_mul_f32 v[104:105], v[104:105], v[186:187] op_sel_hi:[1,0]
	v_pk_mul_f32 v[98:99], v[98:99], v[140:141]
	v_cvt_pk_bf16_f32 v95, v104, v105
	v_cvt_pk_bf16_f32 v96, v96, v97
	v_cvt_pk_bf16_f32 v97, v106, v107
	global_store_dwordx4 v[110:111], v[94:97], off offset:256
	v_pk_mul_f32 v[92:93], v[92:93], v[144:145]
	v_pk_mul_f32 v[90:91], v[90:91], v[142:143]
	v_or_b32_e32 v94, 32, v167
	v_mad_i64_i32 v[94:95], s[8:9], s6, v94, 0
	v_pk_mul_f32 v[96:97], v[100:101], v[146:147]
	v_lshl_add_u64 v[94:95], v[94:95], 1, v[180:181]
	v_pk_mul_f32 v[96:97], v[96:97], v[174:175] op_sel_hi:[1,0]
	v_pk_mul_f32 v[98:99], v[98:99], v[174:175] op_sel_hi:[1,0]
	v_pk_mul_f32 v[100:101], v[92:93], v[174:175] op_sel_hi:[1,0]
	v_pk_mul_f32 v[92:93], v[90:91], v[174:175] op_sel_hi:[1,0]
	v_cvt_pk_bf16_f32 v90, v98, v99
	v_cvt_pk_bf16_f32 v91, v96, v97
	v_pk_mul_f32 v[86:87], v[86:87], v[148:149]
	v_pk_mul_f32 v[80:81], v[80:81], v[154:155]
	v_pk_mul_f32 v[78:79], v[78:79], v[150:151]
	v_cvt_pk_bf16_f32 v92, v92, v93
	v_cvt_pk_bf16_f32 v93, v100, v101
	global_store_dwordx4 v[94:95], v[90:93], off
	v_pk_mul_f32 v[88:89], v[88:89], v[152:153]
	v_pk_mul_f32 v[86:87], v[86:87], v[184:185] op_sel_hi:[1,0]
	v_pk_mul_f32 v[90:91], v[80:81], v[184:185] op_sel_hi:[1,0]
	v_pk_mul_f32 v[80:81], v[78:79], v[184:185] op_sel_hi:[1,0]
	v_cvt_pk_bf16_f32 v78, v86, v87
	v_pk_mul_f32 v[88:89], v[88:89], v[184:185] op_sel_hi:[1,0]
	v_pk_mul_f32 v[82:83], v[82:83], v[140:141]
	v_cvt_pk_bf16_f32 v79, v88, v89
	v_cvt_pk_bf16_f32 v80, v80, v81
	v_cvt_pk_bf16_f32 v81, v90, v91
	global_store_dwordx4 v[94:95], v[78:81], off offset:256
	v_pk_mul_f32 v[76:77], v[76:77], v[144:145]
	v_pk_mul_f32 v[74:75], v[74:75], v[142:143]
	v_or_b32_e32 v78, 48, v167
	v_mad_i64_i32 v[78:79], s[8:9], s6, v78, 0
	v_pk_mul_f32 v[80:81], v[84:85], v[146:147]
	v_lshl_add_u64 v[78:79], v[78:79], 1, v[180:181]
	v_pk_mul_f32 v[80:81], v[80:81], v[164:165] op_sel_hi:[1,0]
	v_pk_mul_f32 v[82:83], v[82:83], v[164:165] op_sel_hi:[1,0]
	v_pk_mul_f32 v[84:85], v[76:77], v[164:165] op_sel_hi:[1,0]
	v_pk_mul_f32 v[76:77], v[74:75], v[164:165] op_sel_hi:[1,0]
	v_cvt_pk_bf16_f32 v74, v82, v83
	v_cvt_pk_bf16_f32 v75, v80, v81
	v_pk_mul_f32 v[70:71], v[70:71], v[148:149]
	v_pk_mul_f32 v[68:69], v[68:69], v[154:155]
	v_pk_mul_f32 v[66:67], v[66:67], v[150:151]
	v_cvt_pk_bf16_f32 v76, v76, v77
	v_cvt_pk_bf16_f32 v77, v84, v85
	global_store_dwordx4 v[78:79], v[74:77], off
	v_pk_mul_f32 v[72:73], v[72:73], v[152:153]
	v_pk_mul_f32 v[70:71], v[70:71], v[170:171] op_sel_hi:[1,0]
	v_pk_mul_f32 v[74:75], v[68:69], v[170:171] op_sel_hi:[1,0]
	v_pk_mul_f32 v[68:69], v[66:67], v[170:171] op_sel_hi:[1,0]
	v_cvt_pk_bf16_f32 v66, v70, v71
	v_pk_mul_f32 v[72:73], v[72:73], v[170:171] op_sel_hi:[1,0]
	v_pk_mul_f32 v[64:65], v[64:65], v[146:147]
	v_cvt_pk_bf16_f32 v67, v72, v73
	v_cvt_pk_bf16_f32 v68, v68, v69
	v_cvt_pk_bf16_f32 v69, v74, v75
	global_store_dwordx4 v[78:79], v[66:69], off offset:256
	v_pk_mul_f32 v[62:63], v[62:63], v[140:141]
	v_pk_mul_f32 v[60:61], v[60:61], v[144:145]
	v_add_u32_e32 v66, 0x80, v167
	v_mad_i64_i32 v[66:67], s[8:9], s6, v66, 0
	v_pk_mul_f32 v[58:59], v[58:59], v[142:143]
	v_lshl_add_u64 v[66:67], v[66:67], 1, v[180:181]
	v_pk_mul_f32 v[64:65], v[64:65], v[172:173] op_sel_hi:[1,0]
	v_pk_mul_f32 v[62:63], v[62:63], v[172:173] op_sel_hi:[1,0]
	v_pk_mul_f32 v[68:69], v[60:61], v[172:173] op_sel_hi:[1,0]
	v_pk_mul_f32 v[60:61], v[58:59], v[172:173] op_sel_hi:[1,0]
	v_cvt_pk_bf16_f32 v58, v62, v63
	v_cvt_pk_bf16_f32 v59, v64, v65
	v_pk_mul_f32 v[54:55], v[54:55], v[148:149]
	v_pk_mul_f32 v[48:49], v[48:49], v[154:155]
	v_pk_mul_f32 v[46:47], v[46:47], v[150:151]
	v_cvt_pk_bf16_f32 v60, v60, v61
	v_cvt_pk_bf16_f32 v61, v68, v69
	global_store_dwordx4 v[66:67], v[58:61], off
	v_pk_mul_f32 v[56:57], v[56:57], v[152:153]
	v_pk_mul_f32 v[54:55], v[54:55], v[182:183] op_sel_hi:[1,0]
	v_pk_mul_f32 v[58:59], v[48:49], v[182:183] op_sel_hi:[1,0]
	v_pk_mul_f32 v[48:49], v[46:47], v[182:183] op_sel_hi:[1,0]
	v_cvt_pk_bf16_f32 v46, v54, v55
	v_pk_mul_f32 v[56:57], v[56:57], v[182:183] op_sel_hi:[1,0]
	v_pk_mul_f32 v[50:51], v[50:51], v[140:141]
	v_cvt_pk_bf16_f32 v47, v56, v57
	v_cvt_pk_bf16_f32 v48, v48, v49
	v_cvt_pk_bf16_f32 v49, v58, v59
	global_store_dwordx4 v[66:67], v[46:49], off offset:256
	v_pk_mul_f32 v[44:45], v[44:45], v[144:145]
	v_pk_mul_f32 v[42:43], v[42:43], v[142:143]
	v_add_u32_e32 v46, 0x90, v167
	v_mad_i64_i32 v[46:47], s[8:9], s6, v46, 0
	v_pk_mul_f32 v[48:49], v[52:53], v[146:147]
	v_lshl_add_u64 v[46:47], v[46:47], 1, v[180:181]
	v_pk_mul_f32 v[48:49], v[48:49], v[162:163] op_sel_hi:[1,0]
	v_pk_mul_f32 v[50:51], v[50:51], v[162:163] op_sel_hi:[1,0]
	v_pk_mul_f32 v[52:53], v[44:45], v[162:163] op_sel_hi:[1,0]
	v_pk_mul_f32 v[44:45], v[42:43], v[162:163] op_sel_hi:[1,0]
	v_cvt_pk_bf16_f32 v42, v50, v51
	v_cvt_pk_bf16_f32 v43, v48, v49
	v_pk_mul_f32 v[38:39], v[38:39], v[148:149]
	v_pk_mul_f32 v[32:33], v[32:33], v[154:155]
	v_pk_mul_f32 v[30:31], v[30:31], v[150:151]
	v_cvt_pk_bf16_f32 v44, v44, v45
	v_cvt_pk_bf16_f32 v45, v52, v53
	global_store_dwordx4 v[46:47], v[42:45], off
	v_pk_mul_f32 v[40:41], v[40:41], v[152:153]
	v_pk_mul_f32 v[38:39], v[38:39], v[168:169] op_sel_hi:[1,0]
	v_pk_mul_f32 v[42:43], v[32:33], v[168:169] op_sel_hi:[1,0]
	v_pk_mul_f32 v[32:33], v[30:31], v[168:169] op_sel_hi:[1,0]
	v_cvt_pk_bf16_f32 v30, v38, v39
	v_pk_mul_f32 v[40:41], v[40:41], v[168:169] op_sel_hi:[1,0]
	v_pk_mul_f32 v[34:35], v[34:35], v[140:141]
	v_cvt_pk_bf16_f32 v31, v40, v41
	v_cvt_pk_bf16_f32 v32, v32, v33
	v_cvt_pk_bf16_f32 v33, v42, v43
	global_store_dwordx4 v[46:47], v[30:33], off offset:256
	v_pk_mul_f32 v[28:29], v[28:29], v[144:145]
	v_pk_mul_f32 v[26:27], v[26:27], v[142:143]
	v_add_u32_e32 v30, 0xa0, v167
	v_mad_i64_i32 v[30:31], s[8:9], s6, v30, 0
	v_pk_mul_f32 v[32:33], v[36:37], v[146:147]
	v_lshl_add_u64 v[30:31], v[30:31], 1, v[180:181]
	v_pk_mul_f32 v[32:33], v[32:33], v[160:161] op_sel_hi:[1,0]
	v_pk_mul_f32 v[34:35], v[34:35], v[160:161] op_sel_hi:[1,0]
	v_pk_mul_f32 v[36:37], v[28:29], v[160:161] op_sel_hi:[1,0]
	v_pk_mul_f32 v[28:29], v[26:27], v[160:161] op_sel_hi:[1,0]
	v_cvt_pk_bf16_f32 v26, v34, v35
	v_cvt_pk_bf16_f32 v27, v32, v33
	v_pk_mul_f32 v[22:23], v[22:23], v[148:149]
	v_pk_mul_f32 v[16:17], v[16:17], v[154:155]
	v_pk_mul_f32 v[14:15], v[14:15], v[150:151]
	v_cvt_pk_bf16_f32 v28, v28, v29
	v_cvt_pk_bf16_f32 v29, v36, v37
	global_store_dwordx4 v[30:31], v[26:29], off
	v_pk_mul_f32 v[24:25], v[24:25], v[152:153]
	v_pk_mul_f32 v[22:23], v[22:23], v[166:167] op_sel_hi:[1,0]
	v_pk_mul_f32 v[26:27], v[16:17], v[166:167] op_sel_hi:[1,0]
	v_pk_mul_f32 v[16:17], v[14:15], v[166:167] op_sel_hi:[1,0]
	v_cvt_pk_bf16_f32 v14, v22, v23
	v_pk_mul_f32 v[24:25], v[24:25], v[166:167] op_sel_hi:[1,0]
	v_pk_mul_f32 v[18:19], v[18:19], v[140:141]
	v_cvt_pk_bf16_f32 v15, v24, v25
	v_cvt_pk_bf16_f32 v16, v16, v17
	v_cvt_pk_bf16_f32 v17, v26, v27
	global_store_dwordx4 v[30:31], v[14:17], off offset:256
	v_pk_mul_f32 v[12:13], v[12:13], v[144:145]
	v_pk_mul_f32 v[10:11], v[10:11], v[142:143]
	v_add_u32_e32 v14, 0xb0, v167
	v_mad_i64_i32 v[14:15], s[6:7], s6, v14, 0
	v_pk_mul_f32 v[16:17], v[20:21], v[146:147]
	v_lshl_add_u64 v[14:15], v[14:15], 1, v[180:181]
	v_pk_mul_f32 v[16:17], v[16:17], v[156:157] op_sel_hi:[1,0]
	v_pk_mul_f32 v[18:19], v[18:19], v[156:157] op_sel_hi:[1,0]
	v_pk_mul_f32 v[20:21], v[12:13], v[156:157] op_sel_hi:[1,0]
	v_pk_mul_f32 v[12:13], v[10:11], v[156:157] op_sel_hi:[1,0]
	v_cvt_pk_bf16_f32 v10, v18, v19
	v_cvt_pk_bf16_f32 v11, v16, v17
	v_pk_mul_f32 v[4:5], v[4:5], v[154:155]
	v_pk_mul_f32 v[2:3], v[2:3], v[150:151]
	v_cvt_pk_bf16_f32 v12, v12, v13
	v_cvt_pk_bf16_f32 v13, v20, v21
	global_store_dwordx4 v[14:15], v[10:13], off
	v_pk_mul_f32 v[8:9], v[8:9], v[152:153]
	v_pk_mul_f32 v[6:7], v[6:7], v[148:149]
	v_pk_mul_f32 v[10:11], v[4:5], v[158:159] op_sel_hi:[1,0]
	v_pk_mul_f32 v[4:5], v[2:3], v[158:159] op_sel_hi:[1,0]
	s_andn2_b64 vcc, exec, s[4:5]
	s_mov_b64 s[4:5], -1
	v_pk_mul_f32 v[8:9], v[8:9], v[158:159] op_sel_hi:[1,0]
	v_pk_mul_f32 v[6:7], v[6:7], v[158:159] op_sel_hi:[1,0]
	s_nop 0
	v_cvt_pk_bf16_f32 v2, v6, v7
	v_cvt_pk_bf16_f32 v3, v8, v9
	v_cvt_pk_bf16_f32 v4, v4, v5
	v_cvt_pk_bf16_f32 v5, v10, v11
	global_store_dwordx4 v[14:15], v[2:5], off offset:256
	s_cbranch_vccnz .LBB0_403
	s_andn2_b64 vcc, exec, s[50:51]
	s_cbranch_vccnz .LBB0_402
	s_barrier
	s_branch .LBB0_402
.LBB0_491:
	s_waitcnt vmcnt(0)
	s_mov_b64 s[14:15], s[0:1]
	v_readlane_b32 s20, v255, 45
	v_readlane_b32 s22, v255, 39
	v_readlane_b32 s0, v255, 41
	v_readlane_b32 s12, v255, 37
	v_readlane_b32 s21, v255, 46
	v_readlane_b32 s23, v255, 40
	v_readlane_b32 s1, v255, 42
	v_readlane_b32 s13, v255, 38
	s_barrier
